# P5_fullline_FR
# speedup vs baseline: 1.0028x; 1.0028x over previous
; template <class Epi, class Sched, bool ALIGN_EPI = false, bool SP2 = false>
; __device__ __forceinline__ void gemm_phase(PG8_LAS unsigned char* lds, const Gemm g, const Sched& S, const Epi& E) {
;     ...
;     const int tid = tid_, wid = __builtin_amdgcn_readfirstlane(tid >> 6), lane = tid & 63, wr = wid >> 2, wc = wid & 3, fr = lane & 15, fq = lane >> 4;
;     const int K = g.K, nt = K / BK;
;     unsigned voffA[2], voffB[2];
; #pragma unroll
;     for (int i = 0; i < 2; ++i) { int R, C; stage_rc(tid * 16 + i * 8192, R, C); const int Rb = Epi::PERM ? ((R & ~31) + perm32(R & 31)) : R;
;         voffA[i] = (unsigned)(R * K + C) * 2u; voffB[i] = (unsigned)(Rb * K + C) * 2u; }
;     const size_t kstep = (size_t)(BK * 2);
;     const size_t hstep = (size_t)HALF * K * 2;
;     const size_t tstep = 2 * hstep;
;     const unsigned ldsw = (unsigned)wid * 1024u;
;     const int aoff = lds_byte(wr * 64 + fr, fq * 8), boff = lds_byte(wc * 32 + fr, fq * 8);
;     ...
;     Unit cur, nxt; int ui = 0;
;     if (!S.next(0, cur)) return;
;     f32x4 acc[2][2][4][2];
; #pragma unroll
;     for (int a = 0; a < 2; ++a)
; #pragma unroll
;         for (int b = 0; b < 2; ++b)
; #pragma unroll
;             for (int m = 0; m < 4; ++m)
; #pragma unroll
;                 for (int n = 0; n < 2; ++n) acc[a][b][m][n] = (f32x4){0.f, 0.f, 0.f, 0.f};
;     bf16x8 At[4][2], B0[2][2], B1[2][2];
;     const char* cA = (const char*)g.A + (size_t)cur.pm * tstep; const char* cB = (const char*)g.Bt + (size_t)cur.pn * tstep;
;     S.a_ready(cur);
;     if constexpr (SP2) {
;         PG8_STAGE(PG8_SB(0, 0), cB, voffB); PG8_STAGE(PG8_SB(0, 1), cB + hstep, voffB); PG8_STAGE(PG8_SA(0, 0), cA, voffA); PG8_STAGE(PG8_SA(0, 1), cA + hstep, voffA);
;         if (wr == 1) PG8_BAR;
;         PG8_WAIT_V(2); PG8_BAR;
;         PG8_STAGE(PG8_SB(1, 0), cB + kstep, voffB); PG8_STAGE(PG8_SA(1, 0), cA + kstep, voffA); PG8_STAGE(PG8_SB(1, 1), cB + hstep + kstep, voffB);
;         PG8_WAIT_V(6); PG8_BAR;
;     } else {
;         PG8_STAGE(PG8_SB(0, 0), cB, voffB); PG8_STAGE(PG8_SA(0, 0), cA, voffA); PG8_STAGE(PG8_SB(0, 1), cB + hstep, voffB); PG8_STAGE(PG8_SA(0, 1), cA + hstep, voffA);
;         if (wr == 1) PG8_BAR;
;         PG8_WAIT_V(4); PG8_BAR;
;         PG8_STAGE(PG8_SB(1, 0), cB + kstep, voffB); PG8_STAGE(PG8_SA(1, 0), cA + kstep, voffA); PG8_STAGE(PG8_SB(1, 1), cB + hstep + kstep, voffB);
;         PG8_WAIT_V(6); PG8_BAR;
.LBB0_769:
	s_cmp_lt_i32 s70, 6
	s_cselect_b64 s[4:5], -1, 0
	s_and_b64 s[4:5], s[4:5], s[0:1]
	s_andn2_b64 vcc, exec, s[4:5]
	s_cbranch_vccnz .LBB0_786
	v_writelane_b32 v253, s4, 0
	v_writelane_b32 v253, s5, 1
	v_writelane_b32 v253, s6, 2
	v_writelane_b32 v253, s7, 3
	v_writelane_b32 v253, s8, 4
	v_writelane_b32 v253, s9, 5
	v_writelane_b32 v253, s10, 6
	v_writelane_b32 v253, s11, 7
	v_writelane_b32 v253, s12, 8
	v_writelane_b32 v253, s13, 9
	v_writelane_b32 v253, s14, 10
	v_writelane_b32 v253, s15, 11
	v_writelane_b32 v253, s16, 12
	v_writelane_b32 v253, s17, 13
	v_writelane_b32 v253, s18, 14
	v_writelane_b32 v253, s19, 15
	v_writelane_b32 v253, s20, 16
	v_writelane_b32 v253, s21, 17
	v_writelane_b32 v253, s22, 18
	v_writelane_b32 v253, s23, 19
	v_writelane_b32 v253, s24, 20
	v_writelane_b32 v253, s25, 21
	v_writelane_b32 v253, s26, 22
	v_writelane_b32 v253, s27, 23
	v_writelane_b32 v253, s28, 24
	v_writelane_b32 v253, s29, 25
	v_writelane_b32 v253, s30, 26
	v_writelane_b32 v253, s31, 27
	v_writelane_b32 v253, s32, 28
	v_writelane_b32 v253, s33, 29
	v_writelane_b32 v253, s34, 30
	v_writelane_b32 v253, s35, 31
	v_writelane_b32 v253, s36, 32
	v_writelane_b32 v253, s37, 33
	v_writelane_b32 v253, s38, 34
	v_writelane_b32 v253, s39, 35
	v_writelane_b32 v253, s40, 36
	v_writelane_b32 v253, s41, 37
	v_writelane_b32 v253, s42, 38
	v_writelane_b32 v253, s43, 39
	v_writelane_b32 v253, s44, 40
	v_writelane_b32 v253, s45, 41
	v_writelane_b32 v253, s46, 42
	v_writelane_b32 v253, s47, 43
	v_writelane_b32 v253, s48, 44
	v_writelane_b32 v253, s49, 45
	v_writelane_b32 v253, s50, 46
	v_writelane_b32 v253, s51, 47
	v_writelane_b32 v253, s52, 48
	v_writelane_b32 v253, s53, 49
	v_writelane_b32 v253, s54, 50
	v_writelane_b32 v253, s55, 51
	v_writelane_b32 v253, s56, 52
	v_writelane_b32 v253, s57, 53
	v_writelane_b32 v253, s58, 54
	v_writelane_b32 v253, s59, 55
	s_mov_b32 s40, vcc_lo
	s_mov_b32 s41, vcc_hi
	v_writelane_b32 v253, s40, 60
	v_writelane_b32 v253, s41, 61
	v_lshrrev_b32_e32 v254, 6, v185
	v_readlane_b32 s14, v244, 4
	v_readfirstlane_b32 s36, v254
	s_nop 3
	s_lshr_b32 s37, s36, 2
	s_and_b32 s38, s36, 3
	s_lshl_b32 s35, s36, 10
	s_add_u32 s10, s76, 0x6800000
	s_addc_u32 s11, s77, 0
	s_add_u32 s12, s76, 0x2500000
	s_addc_u32 s13, s77, 0
	s_mov_b32 s16, 0
	s_mul_i32 s40, s16, s14
	s_add_u32 s40, s40, s2
	s_cmp_lt_u32 s40, 2816
	s_cselect_b32 s44, 1, 0
	s_min_u32 s40, s40, 2815
	s_and_b32 s41, s40, 7
	s_lshr_b32 s42, s40, 3
	s_mul_i32 s41, s41, 352
	s_add_u32 s41, s41, s42
	s_mul_hi_u32 s42, s41, 0xba2e8c
	s_mul_i32 s43, s42, 352
	s_sub_u32 s43, s41, s43
	s_and_b32 s40, s43, 7
	s_lshl_b32 s42, s42, 3
	s_add_u32 s17, s42, s40
	s_lshr_b32 s18, s43, 3
	s_cmp_eq_u32 s44, 0
	s_cbranch_scc1 .Lp5_exit
	v_and_b32_e32 v254, 63, v185
	v_and_b32_e32 v255, 15, v254
	v_lshrrev_b32_e32 v226, 1, v255
	v_lshrrev_b32_e32 v227, 4, v254
	v_xor_b32_e32 v226, v226, v227
	v_lshlrev_b32_e32 v255, 7, v255
	v_lshl_or_b32 v255, v226, 4, v255
	s_lshl_b32 s40, s37, 13
	s_lshl_b32 s41, s38, 12
	s_add_u32 s41, s41, 0x10000
	v_add_u32_e32 v245, s40, v255
	v_add_u32_e32 v247, s41, v255
	v_xor_b32_e32 v246, 64, v245
	v_xor_b32_e32 v248, 64, v247
	v_lshrrev_b32_e32 v255, 3, v254
	v_and_b32_e32 v226, 7, v254
	s_and_b32 s40, s36, 1
	s_lshl_b32 s40, s40, 2
	v_lshrrev_b32_e32 v227, 1, v255
	v_add_u32_e32 v227, s40, v227
	v_xor_b32_e32 v226, v226, v227
	v_lshlrev_b32_e32 v226, 4, v226
	s_lshl_b32 s40, s36, 3
	v_add_u32_e32 v227, s40, v255
	v_mul_u32_u24_e32 v227, 0x1000, v227
	v_add_u32_e32 v249, v227, v226
	v_add_u32_e32 v250, 0x40000, v249
	s_and_b32 s40, s36, 3
	s_lshl_b32 s40, s40, 3
	v_add_u32_e32 v227, s40, v255
	v_lshrrev_b32_e32 v254, 4, v227
	v_lshlrev_b32_e32 v254, 2, v254
	v_and_b32_e32 v255, 3, v227
	v_add_u32_e32 v254, v254, v255
	v_and_b32_e32 v227, 12, v227
	v_lshl_add_u32 v254, v227, 1, v254
	s_lshr_b32 s40, s36, 2
	s_lshl_b32 s40, s40, 5
	v_add_u32_e32 v254, s40, v254
	v_mul_u32_u24_e32 v254, 0x1000, v254
	v_add_u32_e32 v251, v254, v226
	v_add_u32_e32 v252, 0x40000, v251
	s_mul_i32 s40, s17, 0x100000
	s_add_u32 s22, s10, s40
	s_addc_u32 s23, s11, 0
	s_mul_i32 s40, s18, 0x100000
	s_add_u32 s24, s12, s40
	s_addc_u32 s25, s13, 0
	s_add_u32 s30, s22, 0
	s_addc_u32 s31, s23, 0
	s_add_u32 s32, s24, 0
	s_addc_u32 s33, s25, 0
	s_add_u32 s56, s30, 0x80000
	s_addc_u32 s57, s31, 0
	s_add_u32 s58, s32, 0x80000
	s_addc_u32 s59, s33, 0
	s_add_i32 m0, s35, 0x0
	s_nop 0
	global_load_lds_dwordx4 v249, s[30:31]
	s_add_i32 m0, s35, 0x2000
	s_nop 0
	global_load_lds_dwordx4 v250, s[30:31]
	s_add_i32 m0, s35, 0x10000
	s_nop 0
	global_load_lds_dwordx4 v251, s[32:33]
	s_add_i32 m0, s35, 0x12000
	s_nop 0
	global_load_lds_dwordx4 v252, s[32:33]
	s_add_i32 m0, s35, 0x4000
	s_nop 0
	global_load_lds_dwordx4 v249, s[56:57]
	s_add_i32 m0, s35, 0x6000
	s_nop 0
	global_load_lds_dwordx4 v250, s[56:57]
	s_add_i32 m0, s35, 0x14000
	s_nop 0
	global_load_lds_dwordx4 v251, s[58:59]
	s_add_i32 m0, s35, 0x16000
	s_nop 0
	global_load_lds_dwordx4 v252, s[58:59]
	s_add_u32 s30, s30, 128
	s_addc_u32 s31, s31, 0
	s_add_u32 s56, s56, 128
	s_addc_u32 s57, s57, 0
	s_add_u32 s32, s32, 128
	s_addc_u32 s33, s33, 0
	s_add_u32 s58, s58, 128
	s_addc_u32 s59, s59, 0
	s_add_i32 m0, s35, 0x8000
	s_nop 0
	global_load_lds_dwordx4 v249, s[30:31]
	s_add_i32 m0, s35, 0xa000
	s_nop 0
	global_load_lds_dwordx4 v250, s[30:31]
	s_add_i32 m0, s35, 0x1c000
	s_nop 0
	global_load_lds_dwordx4 v251, s[58:59]
	s_add_i32 m0, s35, 0x1e000
	s_nop 0
	global_load_lds_dwordx4 v252, s[58:59]
	s_add_i32 m0, s35, 0xc000
	s_nop 0
	global_load_lds_dwordx4 v249, s[56:57]
	s_add_i32 m0, s35, 0xe000
	s_nop 0
	global_load_lds_dwordx4 v250, s[56:57]
	s_add_i32 m0, s35, 0x18000
	s_nop 0
	global_load_lds_dwordx4 v251, s[32:33]
	s_add_i32 m0, s35, 0x1a000
	s_nop 0
	global_load_lds_dwordx4 v252, s[32:33]
	s_add_u32 s30, s30, 128
	s_addc_u32 s31, s31, 0
	s_add_u32 s56, s56, 128
	s_addc_u32 s57, s57, 0
	s_add_u32 s32, s32, 128
	s_addc_u32 s33, s33, 0
	s_add_u32 s58, s58, 128
	s_addc_u32 s59, s59, 0
	s_waitcnt vmcnt(12)
	s_barrier
; template <class Epi, class Sched, bool ALIGN_EPI = false, bool SP2 = false>
; __device__ __forceinline__ void gemm_phase(PG8_LAS unsigned char* lds, const Gemm g, const Sched& S, const Epi& E) {
;     ...
;         const bool has_next = S.next(ui + 1, nxt);
;         const char* nA = has_next ? (const char*)g.A + (size_t)nxt.pm * tstep : cA; const char* nB = has_next ? (const char*)g.Bt + (size_t)nxt.pn * tstep : cB;
;         for (int t = 0; t < nt; t += 2) {
;             const bool last = (t == nt - 2);
;             const char* a1 = cA + (size_t)(t + 1) * kstep;
;             const char* a2 = last ? nA : cA + (size_t)(t + 2) * kstep; const char* b2 = last ? nB : cB + (size_t)(t + 2) * kstep;
;             const char* a3 = a2 + kstep; const char* b3 = b2 + kstep;
;             if (last && has_next) S.a_ready(nxt);
;     ...
; #pragma unroll
;         for (int a = 0; a < 2; ++a)
; #pragma unroll
;             for (int b = 0; b < 2; ++b)
; #pragma unroll
;                 for (int m = 0; m < 4; ++m)
; #pragma unroll
;                     for (int n = 0; n < 2; ++n) acc[a][b][m][n] = (f32x4){0.f, 0.f, 0.f, 0.f};
;         cur = nxt; cA = nA; cB = nB; ++ui;
.Lp5_unit:
	s_add_u32 s45, s16, 1
	s_mul_i32 s40, s45, s14
	s_add_u32 s40, s40, s2
	s_cmp_lt_u32 s40, 2816
	s_cselect_b32 s19, 1, 0
	s_min_u32 s40, s40, 2815
	s_and_b32 s41, s40, 7
	s_lshr_b32 s42, s40, 3
	s_mul_i32 s41, s41, 352
	s_add_u32 s41, s41, s42
	s_mul_hi_u32 s42, s41, 0xba2e8c
	s_mul_i32 s43, s42, 352
	s_sub_u32 s43, s41, s43
	s_and_b32 s40, s43, 7
	s_lshl_b32 s42, s42, 3
	s_add_u32 s20, s42, s40
	s_lshr_b32 s21, s43, 3
	s_mul_i32 s40, s20, 0x100000
	s_add_u32 s26, s10, s40
	s_addc_u32 s27, s11, 0
	s_mul_i32 s40, s21, 0x100000
	s_add_u32 s28, s12, s40
	s_addc_u32 s29, s13, 0
	s_cmp_eq_u32 s19, 0
	s_cselect_b32 s26, s22, s26
	s_cselect_b32 s27, s23, s27
	s_cselect_b32 s28, s24, s28
	s_cselect_b32 s29, s25, s29
	s_add_u32 s30, s22, 256
	s_addc_u32 s31, s23, 0
	s_add_u32 s32, s24, 256
	s_addc_u32 s33, s25, 0
	s_add_u32 s56, s30, 0x80000
	s_addc_u32 s57, s31, 0
	s_add_u32 s58, s32, 0x80000
	s_addc_u32 s59, s33, 0
	s_movk_i32 s34, 16
	v_mov_b32_e32 v0, 0
	v_mov_b32_e32 v1, 0
	v_mov_b32_e32 v2, 0
	v_mov_b32_e32 v3, 0
	v_mov_b32_e32 v4, 0
	v_mov_b32_e32 v5, 0
	v_mov_b32_e32 v6, 0
	v_mov_b32_e32 v7, 0
	v_mov_b32_e32 v8, 0
	v_mov_b32_e32 v9, 0
	v_mov_b32_e32 v10, 0
	v_mov_b32_e32 v11, 0
	v_mov_b32_e32 v12, 0
	v_mov_b32_e32 v13, 0
	v_mov_b32_e32 v14, 0
	v_mov_b32_e32 v15, 0
	v_mov_b32_e32 v16, 0
	v_mov_b32_e32 v17, 0
	v_mov_b32_e32 v18, 0
	v_mov_b32_e32 v19, 0
	v_mov_b32_e32 v20, 0
	v_mov_b32_e32 v21, 0
	v_mov_b32_e32 v22, 0
	v_mov_b32_e32 v23, 0
	v_mov_b32_e32 v24, 0
	v_mov_b32_e32 v25, 0
	v_mov_b32_e32 v26, 0
	v_mov_b32_e32 v27, 0
	v_mov_b32_e32 v28, 0
	v_mov_b32_e32 v29, 0
	v_mov_b32_e32 v30, 0
	v_mov_b32_e32 v31, 0
	v_mov_b32_e32 v32, 0
	v_mov_b32_e32 v33, 0
	v_mov_b32_e32 v34, 0
	v_mov_b32_e32 v35, 0
	v_mov_b32_e32 v36, 0
	v_mov_b32_e32 v37, 0
	v_mov_b32_e32 v38, 0
	v_mov_b32_e32 v39, 0
	v_mov_b32_e32 v40, 0
	v_mov_b32_e32 v41, 0
	v_mov_b32_e32 v42, 0
	v_mov_b32_e32 v43, 0
	v_mov_b32_e32 v44, 0
	v_mov_b32_e32 v45, 0
	v_mov_b32_e32 v46, 0
	v_mov_b32_e32 v47, 0
	v_mov_b32_e32 v48, 0
	v_mov_b32_e32 v49, 0
	v_mov_b32_e32 v50, 0
	v_mov_b32_e32 v51, 0
	v_mov_b32_e32 v52, 0
	v_mov_b32_e32 v53, 0
	v_mov_b32_e32 v54, 0
	v_mov_b32_e32 v55, 0
	v_mov_b32_e32 v56, 0
	v_mov_b32_e32 v57, 0
	v_mov_b32_e32 v58, 0
	v_mov_b32_e32 v59, 0
	v_mov_b32_e32 v60, 0
	v_mov_b32_e32 v61, 0
	v_mov_b32_e32 v62, 0
	v_mov_b32_e32 v63, 0
	v_mov_b32_e32 v64, 0
	v_mov_b32_e32 v65, 0
	v_mov_b32_e32 v66, 0
	v_mov_b32_e32 v67, 0
	v_mov_b32_e32 v68, 0
	v_mov_b32_e32 v69, 0
	v_mov_b32_e32 v70, 0
	v_mov_b32_e32 v71, 0
	v_mov_b32_e32 v72, 0
	v_mov_b32_e32 v73, 0
	v_mov_b32_e32 v74, 0
	v_mov_b32_e32 v75, 0
	v_mov_b32_e32 v76, 0
	v_mov_b32_e32 v77, 0
	v_mov_b32_e32 v78, 0
	v_mov_b32_e32 v79, 0
	v_mov_b32_e32 v80, 0
	v_mov_b32_e32 v81, 0
	v_mov_b32_e32 v82, 0
	v_mov_b32_e32 v83, 0
	v_mov_b32_e32 v84, 0
	v_mov_b32_e32 v85, 0
	v_mov_b32_e32 v86, 0
	v_mov_b32_e32 v87, 0
	v_mov_b32_e32 v88, 0
	v_mov_b32_e32 v89, 0
	v_mov_b32_e32 v90, 0
	v_mov_b32_e32 v91, 0
	v_mov_b32_e32 v92, 0
	v_mov_b32_e32 v93, 0
	v_mov_b32_e32 v94, 0
	v_mov_b32_e32 v95, 0
	v_mov_b32_e32 v96, 0
	v_mov_b32_e32 v97, 0
	v_mov_b32_e32 v98, 0
	v_mov_b32_e32 v99, 0
	v_mov_b32_e32 v100, 0
	v_mov_b32_e32 v101, 0
	v_mov_b32_e32 v102, 0
	v_mov_b32_e32 v103, 0
	v_mov_b32_e32 v104, 0
	v_mov_b32_e32 v105, 0
	v_mov_b32_e32 v106, 0
	v_mov_b32_e32 v107, 0
	v_mov_b32_e32 v108, 0
	v_mov_b32_e32 v109, 0
	v_mov_b32_e32 v110, 0
	v_mov_b32_e32 v111, 0
	v_mov_b32_e32 v112, 0
	v_mov_b32_e32 v113, 0
	v_mov_b32_e32 v114, 0
	v_mov_b32_e32 v115, 0
	v_mov_b32_e32 v116, 0
	v_mov_b32_e32 v117, 0
	v_mov_b32_e32 v118, 0
	v_mov_b32_e32 v119, 0
	v_mov_b32_e32 v120, 0
	v_mov_b32_e32 v121, 0
	v_mov_b32_e32 v122, 0
	v_mov_b32_e32 v123, 0
	v_mov_b32_e32 v124, 0
	v_mov_b32_e32 v125, 0
	v_mov_b32_e32 v126, 0
	v_mov_b32_e32 v127, 0
	ds_read_b128 v[194:197], v247 offset:0
	ds_read_b128 v[198:201], v248 offset:0
	ds_read_b128 v[202:205], v247 offset:2048
	ds_read_b128 v[206:209], v248 offset:2048
	ds_read_b128 v[128:131], v245 offset:0
	ds_read_b128 v[132:135], v246 offset:0
	ds_read_b128 v[136:139], v245 offset:2048
	ds_read_b128 v[140:143], v246 offset:2048
	ds_read_b128 v[144:147], v245 offset:4096
	ds_read_b128 v[148:151], v246 offset:4096
	ds_read_b128 v[152:155], v245 offset:6144
	ds_read_b128 v[156:159], v246 offset:6144
; #define PG8_STAGE(bufoff, gbase, voff) do { _Pragma("unroll") for (int _i = 0; _i < 2; ++_i) \
;         __builtin_amdgcn_global_load_lds((const unsigned*)((const char*)(gbase) + (voff)[_i]), (PG8_LAS unsigned*)(lds + (bufoff) + ldsw + _i * 8192), 16, 0, 0); } while (0)
; #define PG8_LDA(dst, b, h) do { _Pragma("unroll") for (int m = 0; m < 4; ++m) _Pragma("unroll") for (int k = 0; k < 2; ++k) dst[m][k] = *(const PG8_LAS bf16x8*)(lds + PG8_SA(b, h) + aoff + m * 2048 + k * 1024); } while (0)
; #define PG8_LDB(dst, b, h) do { _Pragma("unroll") for (int n = 0; n < 2; ++n) _Pragma("unroll") for (int k = 0; k < 2; ++k) dst[n][k] = *(const PG8_LAS bf16x8*)(lds + PG8_SB(b, h) + boff + n * 2048 + k * 1024); } while (0)
; #define PG8_MMA(ai, bj, At, Bt) do { __builtin_amdgcn_s_setprio(1); _Pragma("unroll") for (int m = 0; m < 4; ++m) _Pragma("unroll") for (int n = 0; n < 2; ++n) _Pragma("unroll") for (int k = 0; k < 2; ++k) \
;         acc[ai][bj][m][n] = __builtin_amdgcn_mfma_f32_16x16x32_bf16(Bt[n][k], At[m][k], acc[ai][bj][m][n], 0, 0, 0); __builtin_amdgcn_s_setprio(0); } while (0)
; #define PG8_WAIT_V(n) asm volatile("s_waitcnt vmcnt(" #n ")" ::: "memory")
; #define PG8_WAIT_L(n) asm volatile("s_waitcnt lgkmcnt(" #n ")" ::: "memory")
; #define PG8_BAR __builtin_amdgcn_s_barrier()
; #define PG8_SCHED __builtin_amdgcn_sched_barrier(0)
; template <class Epi, class Sched, bool ALIGN_EPI = false, bool SP2 = false>
; __device__ __forceinline__ void gemm_phase(PG8_LAS unsigned char* lds, const Gemm g, const Sched& S, const Epi& E) {
;     ...
;             PG8_LDB(B0, 0, 0); PG8_LDB(B1, 0, 1); PG8_SCHED; PG8_LDA(At, 0, 0); PG8_STAGE(PG8_SA(1, 1), a1 + hstep, voffA);
;             PG8_WAIT_V(8); PG8_WAIT_L(0); PG8_BAR; PG8_MMA(0, 0, At, B0); PG8_MMA(0, 1, At, B1); PG8_BAR; PG8_SCHED;
;             PG8_LDA(At, 0, 1); PG8_STAGE(PG8_SB(0, 0), b2, voffB); PG8_STAGE(PG8_SB(0, 1), b2 + hstep, voffB); PG8_STAGE(PG8_SA(0, 0), a2, voffA);
;             PG8_WAIT_V(8); PG8_WAIT_L(0); PG8_BAR; PG8_MMA(1, 0, At, B0); PG8_MMA(1, 1, At, B1); PG8_BAR; PG8_SCHED;
.Lp5_kloop:
	s_waitcnt vmcnt(8)
	s_waitcnt lgkmcnt(0)
	s_barrier
	v_mfma_f32_16x16x32_bf16 v[0:3], v[194:197], v[128:131], v[0:3]
	ds_read_b128 v[210:213], v247 offset:16384
	v_mfma_f32_16x16x32_bf16 v[4:7], v[202:205], v[128:131], v[4:7]
	ds_read_b128 v[214:217], v248 offset:16384
	v_mfma_f32_16x16x32_bf16 v[8:11], v[194:197], v[136:139], v[8:11]
	ds_read_b128 v[218:221], v247 offset:18432
	v_mfma_f32_16x16x32_bf16 v[12:15], v[202:205], v[136:139], v[12:15]
	ds_read_b128 v[222:225], v248 offset:18432
	v_mfma_f32_16x16x32_bf16 v[16:19], v[194:197], v[144:147], v[16:19]
	ds_read_b128 v[160:163], v245 offset:16384
	v_mfma_f32_16x16x32_bf16 v[20:23], v[202:205], v[144:147], v[20:23]
	ds_read_b128 v[164:167], v246 offset:16384
	v_mfma_f32_16x16x32_bf16 v[24:27], v[194:197], v[152:155], v[24:27]
	ds_read_b128 v[168:171], v245 offset:18432
	v_mfma_f32_16x16x32_bf16 v[28:31], v[202:205], v[152:155], v[28:31]
	ds_read_b128 v[172:175], v246 offset:18432
	v_mfma_f32_16x16x32_bf16 v[0:3], v[198:201], v[132:135], v[0:3]
	ds_read_b128 v[176:179], v245 offset:20480
	v_mfma_f32_16x16x32_bf16 v[4:7], v[206:209], v[132:135], v[4:7]
	ds_read_b128 v[180:183], v246 offset:20480
	v_mfma_f32_16x16x32_bf16 v[8:11], v[198:201], v[140:143], v[8:11]
	ds_read_b128 v[186:189], v245 offset:22528
	v_mfma_f32_16x16x32_bf16 v[12:15], v[206:209], v[140:143], v[12:15]
	ds_read_b128 v[190:193], v246 offset:22528
	v_mfma_f32_16x16x32_bf16 v[16:19], v[198:201], v[148:151], v[16:19]
	v_mfma_f32_16x16x32_bf16 v[20:23], v[206:209], v[148:151], v[20:23]
	s_add_i32 m0, s35, 0x0
	v_mfma_f32_16x16x32_bf16 v[24:27], v[198:201], v[156:159], v[24:27]
	global_load_lds_dwordx4 v249, s[30:31]
	v_mfma_f32_16x16x32_bf16 v[28:31], v[206:209], v[156:159], v[28:31]
	s_waitcnt lgkmcnt(8)
	v_mfma_f32_16x16x32_bf16 v[32:35], v[210:213], v[128:131], v[32:35]
	v_mfma_f32_16x16x32_bf16 v[36:39], v[218:221], v[128:131], v[36:39]
	v_mfma_f32_16x16x32_bf16 v[40:43], v[210:213], v[136:139], v[40:43]
	v_mfma_f32_16x16x32_bf16 v[44:47], v[218:221], v[136:139], v[44:47]
	s_add_i32 m0, s35, 0x2000
	v_mfma_f32_16x16x32_bf16 v[48:51], v[210:213], v[144:147], v[48:51]
	global_load_lds_dwordx4 v250, s[30:31]
	v_mfma_f32_16x16x32_bf16 v[52:55], v[218:221], v[144:147], v[52:55]
	v_mfma_f32_16x16x32_bf16 v[56:59], v[210:213], v[152:155], v[56:59]
	v_mfma_f32_16x16x32_bf16 v[60:63], v[218:221], v[152:155], v[60:63]
	s_add_i32 m0, s35, 0x10000
	v_mfma_f32_16x16x32_bf16 v[32:35], v[214:217], v[132:135], v[32:35]
	global_load_lds_dwordx4 v251, s[32:33]
	v_mfma_f32_16x16x32_bf16 v[36:39], v[222:225], v[132:135], v[36:39]
	v_mfma_f32_16x16x32_bf16 v[40:43], v[214:217], v[140:143], v[40:43]
	v_mfma_f32_16x16x32_bf16 v[44:47], v[222:225], v[140:143], v[44:47]
	s_add_i32 m0, s35, 0x12000
	v_mfma_f32_16x16x32_bf16 v[48:51], v[214:217], v[148:151], v[48:51]
	global_load_lds_dwordx4 v252, s[32:33]
	v_mfma_f32_16x16x32_bf16 v[52:55], v[222:225], v[148:151], v[52:55]
	v_mfma_f32_16x16x32_bf16 v[56:59], v[214:217], v[156:159], v[56:59]
	v_mfma_f32_16x16x32_bf16 v[60:63], v[222:225], v[156:159], v[60:63]
	s_waitcnt vmcnt(8)
	s_waitcnt lgkmcnt(0)
	s_barrier
	v_mfma_f32_16x16x32_bf16 v[96:99], v[210:213], v[160:163], v[96:99]
	ds_read_b128 v[128:131], v245 offset:32768
	v_mfma_f32_16x16x32_bf16 v[100:103], v[218:221], v[160:163], v[100:103]
	ds_read_b128 v[132:135], v246 offset:32768
	v_mfma_f32_16x16x32_bf16 v[104:107], v[210:213], v[168:171], v[104:107]
	ds_read_b128 v[136:139], v245 offset:34816
	v_mfma_f32_16x16x32_bf16 v[108:111], v[218:221], v[168:171], v[108:111]
	ds_read_b128 v[140:143], v246 offset:34816
	v_mfma_f32_16x16x32_bf16 v[112:115], v[210:213], v[176:179], v[112:115]
	ds_read_b128 v[144:147], v245 offset:36864
	v_mfma_f32_16x16x32_bf16 v[116:119], v[218:221], v[176:179], v[116:119]
	ds_read_b128 v[148:151], v246 offset:36864
	v_mfma_f32_16x16x32_bf16 v[120:123], v[210:213], v[186:189], v[120:123]
	ds_read_b128 v[152:155], v245 offset:38912
	v_mfma_f32_16x16x32_bf16 v[124:127], v[218:221], v[186:189], v[124:127]
	ds_read_b128 v[156:159], v246 offset:38912
	v_mfma_f32_16x16x32_bf16 v[96:99], v[214:217], v[164:167], v[96:99]
	v_mfma_f32_16x16x32_bf16 v[100:103], v[222:225], v[164:167], v[100:103]
	s_add_i32 m0, s35, 0x4000
	v_mfma_f32_16x16x32_bf16 v[104:107], v[214:217], v[172:175], v[104:107]
	global_load_lds_dwordx4 v249, s[56:57]
	v_mfma_f32_16x16x32_bf16 v[108:111], v[222:225], v[172:175], v[108:111]
	v_mfma_f32_16x16x32_bf16 v[112:115], v[214:217], v[180:183], v[112:115]
	v_mfma_f32_16x16x32_bf16 v[116:119], v[222:225], v[180:183], v[116:119]
	s_add_i32 m0, s35, 0x6000
	v_mfma_f32_16x16x32_bf16 v[120:123], v[214:217], v[190:193], v[120:123]
	global_load_lds_dwordx4 v250, s[56:57]
	v_mfma_f32_16x16x32_bf16 v[124:127], v[222:225], v[190:193], v[124:127]
	v_mfma_f32_16x16x32_bf16 v[64:67], v[194:197], v[160:163], v[64:67]
	ds_read_b128 v[210:213], v247 offset:49152
	v_mfma_f32_16x16x32_bf16 v[68:71], v[202:205], v[160:163], v[68:71]
	ds_read_b128 v[214:217], v248 offset:49152
	v_mfma_f32_16x16x32_bf16 v[72:75], v[194:197], v[168:171], v[72:75]
	ds_read_b128 v[218:221], v247 offset:51200
	v_mfma_f32_16x16x32_bf16 v[76:79], v[202:205], v[168:171], v[76:79]
	ds_read_b128 v[222:225], v248 offset:51200
	v_mfma_f32_16x16x32_bf16 v[80:83], v[194:197], v[176:179], v[80:83]
	v_mfma_f32_16x16x32_bf16 v[84:87], v[202:205], v[176:179], v[84:87]
	s_add_i32 m0, s35, 0x14000
	v_mfma_f32_16x16x32_bf16 v[88:91], v[194:197], v[186:189], v[88:91]
	global_load_lds_dwordx4 v251, s[58:59]
	v_mfma_f32_16x16x32_bf16 v[92:95], v[202:205], v[186:189], v[92:95]
	v_mfma_f32_16x16x32_bf16 v[64:67], v[198:201], v[164:167], v[64:67]
	v_mfma_f32_16x16x32_bf16 v[68:71], v[206:209], v[164:167], v[68:71]
	s_add_i32 m0, s35, 0x16000
	v_mfma_f32_16x16x32_bf16 v[72:75], v[198:201], v[172:175], v[72:75]
	global_load_lds_dwordx4 v252, s[58:59]
	v_mfma_f32_16x16x32_bf16 v[76:79], v[206:209], v[172:175], v[76:79]
	s_add_u32 s30, s30, 128
	s_addc_u32 s31, s31, 0
	v_mfma_f32_16x16x32_bf16 v[80:83], v[198:201], v[180:183], v[80:83]
	s_add_u32 s56, s56, 128
	s_addc_u32 s57, s57, 0
	v_mfma_f32_16x16x32_bf16 v[84:87], v[206:209], v[180:183], v[84:87]
	s_add_u32 s32, s32, 128
	s_addc_u32 s33, s33, 0
	v_mfma_f32_16x16x32_bf16 v[88:91], v[198:201], v[190:193], v[88:91]
	s_add_u32 s58, s58, 128
	s_addc_u32 s59, s59, 0
	v_mfma_f32_16x16x32_bf16 v[92:95], v[206:209], v[190:193], v[92:95]
	s_waitcnt vmcnt(8)
	s_waitcnt lgkmcnt(0)
	s_barrier
; #define PG8_STAGE(bufoff, gbase, voff) do { _Pragma("unroll") for (int _i = 0; _i < 2; ++_i) \
;         __builtin_amdgcn_global_load_lds((const unsigned*)((const char*)(gbase) + (voff)[_i]), (PG8_LAS unsigned*)(lds + (bufoff) + ldsw + _i * 8192), 16, 0, 0); } while (0)
; #define PG8_LDA(dst, b, h) do { _Pragma("unroll") for (int m = 0; m < 4; ++m) _Pragma("unroll") for (int k = 0; k < 2; ++k) dst[m][k] = *(const PG8_LAS bf16x8*)(lds + PG8_SA(b, h) + aoff + m * 2048 + k * 1024); } while (0)
; #define PG8_LDB(dst, b, h) do { _Pragma("unroll") for (int n = 0; n < 2; ++n) _Pragma("unroll") for (int k = 0; k < 2; ++k) dst[n][k] = *(const PG8_LAS bf16x8*)(lds + PG8_SB(b, h) + boff + n * 2048 + k * 1024); } while (0)
; #define PG8_MMA(ai, bj, At, Bt) do { __builtin_amdgcn_s_setprio(1); _Pragma("unroll") for (int m = 0; m < 4; ++m) _Pragma("unroll") for (int n = 0; n < 2; ++n) _Pragma("unroll") for (int k = 0; k < 2; ++k) \
;         acc[ai][bj][m][n] = __builtin_amdgcn_mfma_f32_16x16x32_bf16(Bt[n][k], At[m][k], acc[ai][bj][m][n], 0, 0, 0); __builtin_amdgcn_s_setprio(0); } while (0)
; #define PG8_WAIT_V(n) asm volatile("s_waitcnt vmcnt(" #n ")" ::: "memory")
; #define PG8_WAIT_L(n) asm volatile("s_waitcnt lgkmcnt(" #n ")" ::: "memory")
; #define PG8_BAR __builtin_amdgcn_s_barrier()
; #define PG8_SCHED __builtin_amdgcn_sched_barrier(0)
; template <class Epi, class Sched, bool ALIGN_EPI = false, bool SP2 = false>
; __device__ __forceinline__ void gemm_phase(PG8_LAS unsigned char* lds, const Gemm g, const Sched& S, const Epi& E) {
;     ...
;             const char* a2 = last ? nA : cA + (size_t)(t + 2) * kstep; const char* b2 = last ? nB : cB + (size_t)(t + 2) * kstep;
;     ...
;             PG8_LDB(B0, 1, 0); PG8_LDB(B1, 1, 1); PG8_SCHED; PG8_LDA(At, 1, 0); PG8_STAGE(PG8_SA(0, 1), a2 + hstep, voffA);
;             PG8_WAIT_V(8); PG8_WAIT_L(0); PG8_BAR; PG8_MMA(0, 0, At, B0); PG8_MMA(0, 1, At, B1); PG8_BAR; PG8_SCHED;
;             PG8_LDA(At, 1, 1); PG8_STAGE(PG8_SB(1, 0), b3, voffB); PG8_STAGE(PG8_SB(1, 1), b3 + hstep, voffB); PG8_STAGE(PG8_SA(1, 0), a3, voffA);
;             PG8_WAIT_V(8); PG8_WAIT_L(0); PG8_BAR; PG8_MMA(1, 0, At, B0); PG8_MMA(1, 1, At, B1); PG8_BAR; PG8_SCHED;
	v_mfma_f32_16x16x32_bf16 v[32:35], v[210:213], v[128:131], v[32:35]
	ds_read_b128 v[194:197], v247 offset:32768
	v_mfma_f32_16x16x32_bf16 v[36:39], v[218:221], v[128:131], v[36:39]
	ds_read_b128 v[198:201], v248 offset:32768
	v_mfma_f32_16x16x32_bf16 v[40:43], v[210:213], v[136:139], v[40:43]
	ds_read_b128 v[202:205], v247 offset:34816
	v_mfma_f32_16x16x32_bf16 v[44:47], v[218:221], v[136:139], v[44:47]
	ds_read_b128 v[206:209], v248 offset:34816
	v_mfma_f32_16x16x32_bf16 v[48:51], v[210:213], v[144:147], v[48:51]
	ds_read_b128 v[160:163], v245 offset:49152
	v_mfma_f32_16x16x32_bf16 v[52:55], v[218:221], v[144:147], v[52:55]
	ds_read_b128 v[164:167], v246 offset:49152
	v_mfma_f32_16x16x32_bf16 v[56:59], v[210:213], v[152:155], v[56:59]
	ds_read_b128 v[168:171], v245 offset:51200
	v_mfma_f32_16x16x32_bf16 v[60:63], v[218:221], v[152:155], v[60:63]
	ds_read_b128 v[172:175], v246 offset:51200
	v_mfma_f32_16x16x32_bf16 v[32:35], v[214:217], v[132:135], v[32:35]
	ds_read_b128 v[176:179], v245 offset:53248
	v_mfma_f32_16x16x32_bf16 v[36:39], v[222:225], v[132:135], v[36:39]
	ds_read_b128 v[180:183], v246 offset:53248
	v_mfma_f32_16x16x32_bf16 v[40:43], v[214:217], v[140:143], v[40:43]
	ds_read_b128 v[186:189], v245 offset:55296
	v_mfma_f32_16x16x32_bf16 v[44:47], v[222:225], v[140:143], v[44:47]
	ds_read_b128 v[190:193], v246 offset:55296
	v_mfma_f32_16x16x32_bf16 v[48:51], v[214:217], v[148:151], v[48:51]
	v_mfma_f32_16x16x32_bf16 v[52:55], v[222:225], v[148:151], v[52:55]
	s_add_i32 m0, s35, 0x8000
	v_mfma_f32_16x16x32_bf16 v[56:59], v[214:217], v[156:159], v[56:59]
	global_load_lds_dwordx4 v249, s[30:31]
	v_mfma_f32_16x16x32_bf16 v[60:63], v[222:225], v[156:159], v[60:63]
	s_waitcnt lgkmcnt(8)
	v_mfma_f32_16x16x32_bf16 v[0:3], v[194:197], v[128:131], v[0:3]
	v_mfma_f32_16x16x32_bf16 v[4:7], v[202:205], v[128:131], v[4:7]
	v_mfma_f32_16x16x32_bf16 v[8:11], v[194:197], v[136:139], v[8:11]
	v_mfma_f32_16x16x32_bf16 v[12:15], v[202:205], v[136:139], v[12:15]
	s_add_i32 m0, s35, 0xa000
	v_mfma_f32_16x16x32_bf16 v[16:19], v[194:197], v[144:147], v[16:19]
	global_load_lds_dwordx4 v250, s[30:31]
	v_mfma_f32_16x16x32_bf16 v[20:23], v[202:205], v[144:147], v[20:23]
	v_mfma_f32_16x16x32_bf16 v[24:27], v[194:197], v[152:155], v[24:27]
	v_mfma_f32_16x16x32_bf16 v[28:31], v[202:205], v[152:155], v[28:31]
	s_add_i32 m0, s35, 0x1c000
	v_mfma_f32_16x16x32_bf16 v[0:3], v[198:201], v[132:135], v[0:3]
	global_load_lds_dwordx4 v251, s[58:59]
	v_mfma_f32_16x16x32_bf16 v[4:7], v[206:209], v[132:135], v[4:7]
	v_mfma_f32_16x16x32_bf16 v[8:11], v[198:201], v[140:143], v[8:11]
	v_mfma_f32_16x16x32_bf16 v[12:15], v[206:209], v[140:143], v[12:15]
	s_add_i32 m0, s35, 0x1e000
	v_mfma_f32_16x16x32_bf16 v[16:19], v[198:201], v[148:151], v[16:19]
	global_load_lds_dwordx4 v252, s[58:59]
	v_mfma_f32_16x16x32_bf16 v[20:23], v[206:209], v[148:151], v[20:23]
	v_mfma_f32_16x16x32_bf16 v[24:27], v[198:201], v[156:159], v[24:27]
	v_mfma_f32_16x16x32_bf16 v[28:31], v[206:209], v[156:159], v[28:31]
	s_waitcnt vmcnt(8)
	s_waitcnt lgkmcnt(0)
	s_barrier
	v_mfma_f32_16x16x32_bf16 v[64:67], v[194:197], v[160:163], v[64:67]
	ds_read_b128 v[128:131], v245 offset:0
	v_mfma_f32_16x16x32_bf16 v[68:71], v[202:205], v[160:163], v[68:71]
	ds_read_b128 v[132:135], v246 offset:0
	v_mfma_f32_16x16x32_bf16 v[72:75], v[194:197], v[168:171], v[72:75]
	ds_read_b128 v[136:139], v245 offset:2048
	v_mfma_f32_16x16x32_bf16 v[76:79], v[202:205], v[168:171], v[76:79]
	ds_read_b128 v[140:143], v246 offset:2048
	v_mfma_f32_16x16x32_bf16 v[80:83], v[194:197], v[176:179], v[80:83]
	ds_read_b128 v[144:147], v245 offset:4096
	v_mfma_f32_16x16x32_bf16 v[84:87], v[202:205], v[176:179], v[84:87]
	ds_read_b128 v[148:151], v246 offset:4096
	v_mfma_f32_16x16x32_bf16 v[88:91], v[194:197], v[186:189], v[88:91]
	ds_read_b128 v[152:155], v245 offset:6144
	v_mfma_f32_16x16x32_bf16 v[92:95], v[202:205], v[186:189], v[92:95]
	ds_read_b128 v[156:159], v246 offset:6144
	v_mfma_f32_16x16x32_bf16 v[64:67], v[198:201], v[164:167], v[64:67]
	v_mfma_f32_16x16x32_bf16 v[68:71], v[206:209], v[164:167], v[68:71]
	s_add_i32 m0, s35, 0xc000
	v_mfma_f32_16x16x32_bf16 v[72:75], v[198:201], v[172:175], v[72:75]
	global_load_lds_dwordx4 v249, s[56:57]
	v_mfma_f32_16x16x32_bf16 v[76:79], v[206:209], v[172:175], v[76:79]
	v_mfma_f32_16x16x32_bf16 v[80:83], v[198:201], v[180:183], v[80:83]
	v_mfma_f32_16x16x32_bf16 v[84:87], v[206:209], v[180:183], v[84:87]
	s_add_i32 m0, s35, 0xe000
	v_mfma_f32_16x16x32_bf16 v[88:91], v[198:201], v[190:193], v[88:91]
	global_load_lds_dwordx4 v250, s[56:57]
	v_mfma_f32_16x16x32_bf16 v[92:95], v[206:209], v[190:193], v[92:95]
	v_mfma_f32_16x16x32_bf16 v[96:99], v[210:213], v[160:163], v[96:99]
	ds_read_b128 v[194:197], v247 offset:0
	v_mfma_f32_16x16x32_bf16 v[100:103], v[218:221], v[160:163], v[100:103]
	ds_read_b128 v[198:201], v248 offset:0
	v_mfma_f32_16x16x32_bf16 v[104:107], v[210:213], v[168:171], v[104:107]
	ds_read_b128 v[202:205], v247 offset:2048
	v_mfma_f32_16x16x32_bf16 v[108:111], v[218:221], v[168:171], v[108:111]
	ds_read_b128 v[206:209], v248 offset:2048
	v_mfma_f32_16x16x32_bf16 v[112:115], v[210:213], v[176:179], v[112:115]
	v_mfma_f32_16x16x32_bf16 v[116:119], v[218:221], v[176:179], v[116:119]
	s_add_i32 m0, s35, 0x18000
	v_mfma_f32_16x16x32_bf16 v[120:123], v[210:213], v[186:189], v[120:123]
	global_load_lds_dwordx4 v251, s[32:33]
	v_mfma_f32_16x16x32_bf16 v[124:127], v[218:221], v[186:189], v[124:127]
	v_mfma_f32_16x16x32_bf16 v[96:99], v[214:217], v[164:167], v[96:99]
	v_mfma_f32_16x16x32_bf16 v[100:103], v[222:225], v[164:167], v[100:103]
	s_add_i32 m0, s35, 0x1a000
	v_mfma_f32_16x16x32_bf16 v[104:107], v[214:217], v[172:175], v[104:107]
	global_load_lds_dwordx4 v252, s[32:33]
	v_mfma_f32_16x16x32_bf16 v[108:111], v[222:225], v[172:175], v[108:111]
	s_add_u32 s30, s30, 128
	s_addc_u32 s31, s31, 0
	v_mfma_f32_16x16x32_bf16 v[112:115], v[214:217], v[180:183], v[112:115]
	s_add_u32 s56, s56, 128
	s_addc_u32 s57, s57, 0
	v_mfma_f32_16x16x32_bf16 v[116:119], v[222:225], v[180:183], v[116:119]
	s_add_u32 s32, s32, 128
	s_addc_u32 s33, s33, 0
	v_mfma_f32_16x16x32_bf16 v[120:123], v[214:217], v[190:193], v[120:123]
	s_add_u32 s58, s58, 128
	s_addc_u32 s59, s59, 0
	v_mfma_f32_16x16x32_bf16 v[124:127], v[222:225], v[190:193], v[124:127]
	s_add_i32 s34, s34, -1
	s_cmp_lg_u32 s34, 1
	s_cbranch_scc1 .Lp5_nosw
	s_add_u32 s30, s26, 0
	s_addc_u32 s31, s27, 0
	s_add_u32 s32, s28, 0
	s_addc_u32 s33, s29, 0
	s_add_u32 s56, s30, 0x80000
	s_addc_u32 s57, s31, 0
	s_add_u32 s58, s32, 0x80000
	s_addc_u32 s59, s33, 0
; __device__ __forceinline__ unsigned cvt_pk_bf16(float lo, float hi) { unsigned r; asm volatile("v_cvt_pk_bf16_f32 %0, %1, %2" : "=v"(r) : "v"(lo), "v"(hi)); return r; }
;     __device__ __forceinline__ void operator()(const f32x4 (&acc)[2][2][4][2], const Unit& u, int wr, int wc, int fr, int fq) const {
;         const int row0 = u.pm * BM + wr * 64 + fr, col0 = u.pn * HALF + wc * 32 + 8 * fq;
;         float rsv[2][4];
; #pragma unroll
;         for (int ai = 0; ai < 2; ++ai)
; #pragma unroll
;             for (int m = 0; m < 4; ++m) rsv[ai][m] = ss[row0 + ai * HALF + m * 16];
;         asm volatile("" ::: "memory");
; #pragma unroll
;         for (int ai = 0; ai < 2; ++ai)
; #pragma unroll
;             for (int m = 0; m < 4; ++m) { const int row = row0 + ai * HALF + m * 16; const float rs = __builtin_amdgcn_rsqf(rsv[ai][m] * inv_n + eps);
;                 float a[8];
; #pragma unroll
;                 for (int n = 0; n < 2; ++n)
; #pragma unroll
;                     for (int i = 0; i < 4; ++i) { const float g = acc[ai][0][m][n][i] * rs, up = acc[ai][1][m][n][i] * rs;
;                         a[n * 4 + i] = g * __builtin_amdgcn_rcpf(1.0f + __builtin_amdgcn_exp2f(-1.4426950408889634f * g)) * up; }
;                 u32x4 w; w.x = cvt_pk_bf16(a[0], a[1]); w.y = cvt_pk_bf16(a[2], a[3]); w.z = cvt_pk_bf16(a[4], a[5]); w.w = cvt_pk_bf16(a[6], a[7]);
;                 *(u32x4*)(O + (size_t)row * ldc + col0) = w; }
.Lp5_nosw:
	s_cmp_lg_u32 s34, 0
	s_cbranch_scc1 .Lp5_kloop
	s_waitcnt lgkmcnt(0)
	s_nop 7
	s_nop 7
	v_and_b32_e32 v254, 63, v185
	v_and_b32_e32 v255, 15, v254
	v_lshrrev_b32_e32 v226, 4, v254
	s_lshl_b32 s40, s37, 6
	v_add_u32_e32 v255, s40, v255
	v_lshlrev_b32_e32 v128, 2, v255
	v_mul_u32_u24_e32 v129, 0x2c00, v255
	s_lshl_b32 s41, s38, 6
	v_lshl_add_u32 v129, v226, 4, v129
	v_add_u32_e32 v129, s41, v129
	v_mov_b32_e32 v130, 0x358637bd
	s_lshl_b32 s40, s17, 10
	s_add_u32 s48, s76, s40
	s_addc_u32 s49, s77, 0
	s_mul_i32 s40, s17, 0x2c0000
	s_lshl_b32 s41, s18, 8
	s_add_u32 s40, s40, s41
	s_add_u32 s50, s76, 0xa800000
	s_addc_u32 s51, s77, 0
	s_add_u32 s50, s50, s40
	s_addc_u32 s51, s51, 0
	global_load_dword v134, v128, s[48:49] offset:0
	global_load_dword v135, v128, s[48:49] offset:64
	global_load_dword v136, v128, s[48:49] offset:128
	global_load_dword v137, v128, s[48:49] offset:192
	global_load_dword v138, v128, s[48:49] offset:512
	global_load_dword v139, v128, s[48:49] offset:576
	global_load_dword v140, v128, s[48:49] offset:640
	global_load_dword v141, v128, s[48:49] offset:704
	s_waitcnt vmcnt(0)
	v_fmamk_f32 v131, v134, 0x3a000000, v130
	v_add_u32_e32 v132, 0x0, v129
	v_rsq_f32_e32 v131, v131
	s_nop 0
	v_mul_f32_e32 v0, v0, v131
	v_mul_f32_e32 v1, v1, v131
	v_mul_f32_e32 v2, v2, v131
	v_mul_f32_e32 v3, v3, v131
	v_mul_f32_e32 v4, v4, v131
	v_mul_f32_e32 v5, v5, v131
	v_mul_f32_e32 v6, v6, v131
	v_mul_f32_e32 v7, v7, v131
	v_mul_f32_e32 v32, v32, v131
	v_mul_f32_e32 v33, v33, v131
	v_mul_f32_e32 v34, v34, v131
	v_mul_f32_e32 v35, v35, v131
	v_mul_f32_e32 v36, v36, v131
	v_mul_f32_e32 v37, v37, v131
	v_mul_f32_e32 v38, v38, v131
	v_mul_f32_e32 v39, v39, v131
	v_mul_f32_e32 v144, 0xbfb8aa3b, v0
	v_mul_f32_e32 v145, 0xbfb8aa3b, v1
	v_mul_f32_e32 v146, 0xbfb8aa3b, v2
	v_mul_f32_e32 v147, 0xbfb8aa3b, v3
	v_mul_f32_e32 v148, 0xbfb8aa3b, v4
	v_mul_f32_e32 v149, 0xbfb8aa3b, v5
	v_mul_f32_e32 v150, 0xbfb8aa3b, v6
	v_mul_f32_e32 v151, 0xbfb8aa3b, v7
	v_exp_f32_e32 v144, v144
	v_exp_f32_e32 v145, v145
	v_exp_f32_e32 v146, v146
	v_exp_f32_e32 v147, v147
	v_exp_f32_e32 v148, v148
	v_exp_f32_e32 v149, v149
	v_exp_f32_e32 v150, v150
	v_exp_f32_e32 v151, v151
	v_add_f32_e32 v144, 1.0, v144
	v_add_f32_e32 v145, 1.0, v145
	v_add_f32_e32 v146, 1.0, v146
	v_add_f32_e32 v147, 1.0, v147
	v_add_f32_e32 v148, 1.0, v148
	v_add_f32_e32 v149, 1.0, v149
	v_add_f32_e32 v150, 1.0, v150
	v_add_f32_e32 v151, 1.0, v151
	v_rcp_f32_e32 v144, v144
	v_rcp_f32_e32 v145, v145
	v_rcp_f32_e32 v146, v146
	v_rcp_f32_e32 v147, v147
	v_rcp_f32_e32 v148, v148
	v_rcp_f32_e32 v149, v149
	v_rcp_f32_e32 v150, v150
	v_rcp_f32_e32 v151, v151
	v_mul_f32_e32 v0, v0, v144
	v_mul_f32_e32 v1, v1, v145
	v_mul_f32_e32 v2, v2, v146
	v_mul_f32_e32 v3, v3, v147
	v_mul_f32_e32 v4, v4, v148
	v_mul_f32_e32 v5, v5, v149
	v_mul_f32_e32 v6, v6, v150
	v_mul_f32_e32 v7, v7, v151
	v_mul_f32_e32 v0, v32, v0
	v_mul_f32_e32 v1, v33, v1
	v_mul_f32_e32 v2, v34, v2
	v_mul_f32_e32 v3, v35, v3
	v_mul_f32_e32 v4, v36, v4
	v_mul_f32_e32 v5, v37, v5
	v_mul_f32_e32 v6, v38, v6
	v_mul_f32_e32 v7, v39, v7
	v_cvt_pk_bf16_f32 v152, v0, v1
	v_cvt_pk_bf16_f32 v153, v2, v3
	v_cvt_pk_bf16_f32 v154, v4, v5
	v_cvt_pk_bf16_f32 v155, v6, v7
	s_nop 1
	global_store_dwordx4 v132, v[152:155], s[50:51]
	s_nop 1
	v_fmamk_f32 v131, v135, 0x3a000000, v130
	v_add_u32_e32 v132, 0x2c000, v129
	v_rsq_f32_e32 v131, v131
	s_nop 0
	v_mul_f32_e32 v8, v8, v131
	v_mul_f32_e32 v9, v9, v131
	v_mul_f32_e32 v10, v10, v131
	v_mul_f32_e32 v11, v11, v131
	v_mul_f32_e32 v12, v12, v131
	v_mul_f32_e32 v13, v13, v131
	v_mul_f32_e32 v14, v14, v131
	v_mul_f32_e32 v15, v15, v131
	v_mul_f32_e32 v40, v40, v131
	v_mul_f32_e32 v41, v41, v131
	v_mul_f32_e32 v42, v42, v131
	v_mul_f32_e32 v43, v43, v131
	v_mul_f32_e32 v44, v44, v131
	v_mul_f32_e32 v45, v45, v131
	v_mul_f32_e32 v46, v46, v131
	v_mul_f32_e32 v47, v47, v131
	v_mul_f32_e32 v144, 0xbfb8aa3b, v8
	v_mul_f32_e32 v145, 0xbfb8aa3b, v9
	v_mul_f32_e32 v146, 0xbfb8aa3b, v10
	v_mul_f32_e32 v147, 0xbfb8aa3b, v11
	v_mul_f32_e32 v148, 0xbfb8aa3b, v12
	v_mul_f32_e32 v149, 0xbfb8aa3b, v13
	v_mul_f32_e32 v150, 0xbfb8aa3b, v14
	v_mul_f32_e32 v151, 0xbfb8aa3b, v15
	v_exp_f32_e32 v144, v144
	v_exp_f32_e32 v145, v145
	v_exp_f32_e32 v146, v146
	v_exp_f32_e32 v147, v147
	v_exp_f32_e32 v148, v148
	v_exp_f32_e32 v149, v149
	v_exp_f32_e32 v150, v150
	v_exp_f32_e32 v151, v151
	v_add_f32_e32 v144, 1.0, v144
	v_add_f32_e32 v145, 1.0, v145
	v_add_f32_e32 v146, 1.0, v146
	v_add_f32_e32 v147, 1.0, v147
	v_add_f32_e32 v148, 1.0, v148
	v_add_f32_e32 v149, 1.0, v149
	v_add_f32_e32 v150, 1.0, v150
	v_add_f32_e32 v151, 1.0, v151
	v_rcp_f32_e32 v144, v144
	v_rcp_f32_e32 v145, v145
	v_rcp_f32_e32 v146, v146
	v_rcp_f32_e32 v147, v147
	v_rcp_f32_e32 v148, v148
	v_rcp_f32_e32 v149, v149
	v_rcp_f32_e32 v150, v150
	v_rcp_f32_e32 v151, v151
	v_mul_f32_e32 v8, v8, v144
	v_mul_f32_e32 v9, v9, v145
	v_mul_f32_e32 v10, v10, v146
	v_mul_f32_e32 v11, v11, v147
	v_mul_f32_e32 v12, v12, v148
	v_mul_f32_e32 v13, v13, v149
	v_mul_f32_e32 v14, v14, v150
	v_mul_f32_e32 v15, v15, v151
	v_mul_f32_e32 v8, v40, v8
	v_mul_f32_e32 v9, v41, v9
	v_mul_f32_e32 v10, v42, v10
	v_mul_f32_e32 v11, v43, v11
	v_mul_f32_e32 v12, v44, v12
	v_mul_f32_e32 v13, v45, v13
	v_mul_f32_e32 v14, v46, v14
	v_mul_f32_e32 v15, v47, v15
	v_cvt_pk_bf16_f32 v152, v8, v9
	v_cvt_pk_bf16_f32 v153, v10, v11
	v_cvt_pk_bf16_f32 v154, v12, v13
	v_cvt_pk_bf16_f32 v155, v14, v15
	s_nop 1
	global_store_dwordx4 v132, v[152:155], s[50:51]
	s_nop 1
	v_fmamk_f32 v131, v136, 0x3a000000, v130
	v_add_u32_e32 v132, 0x58000, v129
	v_rsq_f32_e32 v131, v131
	s_nop 0
	v_mul_f32_e32 v16, v16, v131
; __device__ __forceinline__ unsigned cvt_pk_bf16(float lo, float hi) { unsigned r; asm volatile("v_cvt_pk_bf16_f32 %0, %1, %2" : "=v"(r) : "v"(lo), "v"(hi)); return r; }
;     __device__ __forceinline__ void operator()(const f32x4 (&acc)[2][2][4][2], const Unit& u, int wr, int wc, int fr, int fq) const {
;     ...
;         for (int ai = 0; ai < 2; ++ai)
; #pragma unroll
;             for (int m = 0; m < 4; ++m) { const int row = row0 + ai * HALF + m * 16; const float rs = __builtin_amdgcn_rsqf(rsv[ai][m] * inv_n + eps);
;                 float a[8];
; #pragma unroll
;                 for (int n = 0; n < 2; ++n)
; #pragma unroll
;                     for (int i = 0; i < 4; ++i) { const float g = acc[ai][0][m][n][i] * rs, up = acc[ai][1][m][n][i] * rs;
;                         a[n * 4 + i] = g * __builtin_amdgcn_rcpf(1.0f + __builtin_amdgcn_exp2f(-1.4426950408889634f * g)) * up; }
;                 u32x4 w; w.x = cvt_pk_bf16(a[0], a[1]); w.y = cvt_pk_bf16(a[2], a[3]); w.z = cvt_pk_bf16(a[4], a[5]); w.w = cvt_pk_bf16(a[6], a[7]);
;                 *(u32x4*)(O + (size_t)row * ldc + col0) = w; }
	v_mul_f32_e32 v17, v17, v131
	v_mul_f32_e32 v18, v18, v131
	v_mul_f32_e32 v19, v19, v131
	v_mul_f32_e32 v20, v20, v131
	v_mul_f32_e32 v21, v21, v131
	v_mul_f32_e32 v22, v22, v131
	v_mul_f32_e32 v23, v23, v131
	v_mul_f32_e32 v48, v48, v131
	v_mul_f32_e32 v49, v49, v131
	v_mul_f32_e32 v50, v50, v131
	v_mul_f32_e32 v51, v51, v131
	v_mul_f32_e32 v52, v52, v131
	v_mul_f32_e32 v53, v53, v131
	v_mul_f32_e32 v54, v54, v131
	v_mul_f32_e32 v55, v55, v131
	v_mul_f32_e32 v144, 0xbfb8aa3b, v16
	v_mul_f32_e32 v145, 0xbfb8aa3b, v17
	v_mul_f32_e32 v146, 0xbfb8aa3b, v18
	v_mul_f32_e32 v147, 0xbfb8aa3b, v19
	v_mul_f32_e32 v148, 0xbfb8aa3b, v20
	v_mul_f32_e32 v149, 0xbfb8aa3b, v21
	v_mul_f32_e32 v150, 0xbfb8aa3b, v22
	v_mul_f32_e32 v151, 0xbfb8aa3b, v23
	v_exp_f32_e32 v144, v144
	v_exp_f32_e32 v145, v145
	v_exp_f32_e32 v146, v146
	v_exp_f32_e32 v147, v147
	v_exp_f32_e32 v148, v148
	v_exp_f32_e32 v149, v149
	v_exp_f32_e32 v150, v150
	v_exp_f32_e32 v151, v151
	v_add_f32_e32 v144, 1.0, v144
	v_add_f32_e32 v145, 1.0, v145
	v_add_f32_e32 v146, 1.0, v146
	v_add_f32_e32 v147, 1.0, v147
	v_add_f32_e32 v148, 1.0, v148
	v_add_f32_e32 v149, 1.0, v149
	v_add_f32_e32 v150, 1.0, v150
	v_add_f32_e32 v151, 1.0, v151
	v_rcp_f32_e32 v144, v144
	v_rcp_f32_e32 v145, v145
	v_rcp_f32_e32 v146, v146
	v_rcp_f32_e32 v147, v147
	v_rcp_f32_e32 v148, v148
	v_rcp_f32_e32 v149, v149
	v_rcp_f32_e32 v150, v150
	v_rcp_f32_e32 v151, v151
	v_mul_f32_e32 v16, v16, v144
	v_mul_f32_e32 v17, v17, v145
	v_mul_f32_e32 v18, v18, v146
	v_mul_f32_e32 v19, v19, v147
	v_mul_f32_e32 v20, v20, v148
	v_mul_f32_e32 v21, v21, v149
	v_mul_f32_e32 v22, v22, v150
	v_mul_f32_e32 v23, v23, v151
	v_mul_f32_e32 v16, v48, v16
	v_mul_f32_e32 v17, v49, v17
	v_mul_f32_e32 v18, v50, v18
	v_mul_f32_e32 v19, v51, v19
	v_mul_f32_e32 v20, v52, v20
	v_mul_f32_e32 v21, v53, v21
	v_mul_f32_e32 v22, v54, v22
	v_mul_f32_e32 v23, v55, v23
	v_cvt_pk_bf16_f32 v152, v16, v17
	v_cvt_pk_bf16_f32 v153, v18, v19
	v_cvt_pk_bf16_f32 v154, v20, v21
	v_cvt_pk_bf16_f32 v155, v22, v23
	s_nop 1
	global_store_dwordx4 v132, v[152:155], s[50:51]
	s_nop 1
	v_fmamk_f32 v131, v137, 0x3a000000, v130
	v_add_u32_e32 v132, 0x84000, v129
	v_rsq_f32_e32 v131, v131
	s_nop 0
	v_mul_f32_e32 v24, v24, v131
	v_mul_f32_e32 v25, v25, v131
	v_mul_f32_e32 v26, v26, v131
	v_mul_f32_e32 v27, v27, v131
	v_mul_f32_e32 v28, v28, v131
	v_mul_f32_e32 v29, v29, v131
	v_mul_f32_e32 v30, v30, v131
	v_mul_f32_e32 v31, v31, v131
	v_mul_f32_e32 v56, v56, v131
	v_mul_f32_e32 v57, v57, v131
	v_mul_f32_e32 v58, v58, v131
	v_mul_f32_e32 v59, v59, v131
	v_mul_f32_e32 v60, v60, v131
	v_mul_f32_e32 v61, v61, v131
	v_mul_f32_e32 v62, v62, v131
	v_mul_f32_e32 v63, v63, v131
	v_mul_f32_e32 v144, 0xbfb8aa3b, v24
	v_mul_f32_e32 v145, 0xbfb8aa3b, v25
	v_mul_f32_e32 v146, 0xbfb8aa3b, v26
	v_mul_f32_e32 v147, 0xbfb8aa3b, v27
	v_mul_f32_e32 v148, 0xbfb8aa3b, v28
	v_mul_f32_e32 v149, 0xbfb8aa3b, v29
	v_mul_f32_e32 v150, 0xbfb8aa3b, v30
	v_mul_f32_e32 v151, 0xbfb8aa3b, v31
	v_exp_f32_e32 v144, v144
	v_exp_f32_e32 v145, v145
	v_exp_f32_e32 v146, v146
	v_exp_f32_e32 v147, v147
	v_exp_f32_e32 v148, v148
	v_exp_f32_e32 v149, v149
	v_exp_f32_e32 v150, v150
	v_exp_f32_e32 v151, v151
	v_add_f32_e32 v144, 1.0, v144
	v_add_f32_e32 v145, 1.0, v145
	v_add_f32_e32 v146, 1.0, v146
	v_add_f32_e32 v147, 1.0, v147
	v_add_f32_e32 v148, 1.0, v148
	v_add_f32_e32 v149, 1.0, v149
	v_add_f32_e32 v150, 1.0, v150
	v_add_f32_e32 v151, 1.0, v151
	v_rcp_f32_e32 v144, v144
	v_rcp_f32_e32 v145, v145
	v_rcp_f32_e32 v146, v146
	v_rcp_f32_e32 v147, v147
	v_rcp_f32_e32 v148, v148
	v_rcp_f32_e32 v149, v149
	v_rcp_f32_e32 v150, v150
	v_rcp_f32_e32 v151, v151
	v_mul_f32_e32 v24, v24, v144
	v_mul_f32_e32 v25, v25, v145
	v_mul_f32_e32 v26, v26, v146
	v_mul_f32_e32 v27, v27, v147
	v_mul_f32_e32 v28, v28, v148
	v_mul_f32_e32 v29, v29, v149
	v_mul_f32_e32 v30, v30, v150
	v_mul_f32_e32 v31, v31, v151
	v_mul_f32_e32 v24, v56, v24
	v_mul_f32_e32 v25, v57, v25
	v_mul_f32_e32 v26, v58, v26
	v_mul_f32_e32 v27, v59, v27
	v_mul_f32_e32 v28, v60, v28
	v_mul_f32_e32 v29, v61, v29
	v_mul_f32_e32 v30, v62, v30
	v_mul_f32_e32 v31, v63, v31
	v_cvt_pk_bf16_f32 v152, v24, v25
	v_cvt_pk_bf16_f32 v153, v26, v27
	v_cvt_pk_bf16_f32 v154, v28, v29
	v_cvt_pk_bf16_f32 v155, v30, v31
	s_nop 1
	global_store_dwordx4 v132, v[152:155], s[50:51]
	s_nop 1
	v_fmamk_f32 v131, v138, 0x3a000000, v130
	v_add_u32_e32 v132, 0x160000, v129
	v_rsq_f32_e32 v131, v131
	s_nop 0
	v_mul_f32_e32 v64, v64, v131
	v_mul_f32_e32 v65, v65, v131
	v_mul_f32_e32 v66, v66, v131
	v_mul_f32_e32 v67, v67, v131
	v_mul_f32_e32 v68, v68, v131
	v_mul_f32_e32 v69, v69, v131
	v_mul_f32_e32 v70, v70, v131
	v_mul_f32_e32 v71, v71, v131
	v_mul_f32_e32 v96, v96, v131
	v_mul_f32_e32 v97, v97, v131
	v_mul_f32_e32 v98, v98, v131
	v_mul_f32_e32 v99, v99, v131
	v_mul_f32_e32 v100, v100, v131
	v_mul_f32_e32 v101, v101, v131
	v_mul_f32_e32 v102, v102, v131
	v_mul_f32_e32 v103, v103, v131
	v_mul_f32_e32 v144, 0xbfb8aa3b, v64
	v_mul_f32_e32 v145, 0xbfb8aa3b, v65
	v_mul_f32_e32 v146, 0xbfb8aa3b, v66
	v_mul_f32_e32 v147, 0xbfb8aa3b, v67
	v_mul_f32_e32 v148, 0xbfb8aa3b, v68
	v_mul_f32_e32 v149, 0xbfb8aa3b, v69
	v_mul_f32_e32 v150, 0xbfb8aa3b, v70
	v_mul_f32_e32 v151, 0xbfb8aa3b, v71
	v_exp_f32_e32 v144, v144
	v_exp_f32_e32 v145, v145
	v_exp_f32_e32 v146, v146
	v_exp_f32_e32 v147, v147
	v_exp_f32_e32 v148, v148
	v_exp_f32_e32 v149, v149
	v_exp_f32_e32 v150, v150
	v_exp_f32_e32 v151, v151
	v_add_f32_e32 v144, 1.0, v144
	v_add_f32_e32 v145, 1.0, v145
	v_add_f32_e32 v146, 1.0, v146
	v_add_f32_e32 v147, 1.0, v147
	v_add_f32_e32 v148, 1.0, v148
	v_add_f32_e32 v149, 1.0, v149
	v_add_f32_e32 v150, 1.0, v150
; __device__ __forceinline__ unsigned cvt_pk_bf16(float lo, float hi) { unsigned r; asm volatile("v_cvt_pk_bf16_f32 %0, %1, %2" : "=v"(r) : "v"(lo), "v"(hi)); return r; }
;     __device__ __forceinline__ void operator()(const f32x4 (&acc)[2][2][4][2], const Unit& u, int wr, int wc, int fr, int fq) const {
;     ...
;         for (int ai = 0; ai < 2; ++ai)
; #pragma unroll
;             for (int m = 0; m < 4; ++m) { const int row = row0 + ai * HALF + m * 16; const float rs = __builtin_amdgcn_rsqf(rsv[ai][m] * inv_n + eps);
;                 float a[8];
; #pragma unroll
;                 for (int n = 0; n < 2; ++n)
; #pragma unroll
;                     for (int i = 0; i < 4; ++i) { const float g = acc[ai][0][m][n][i] * rs, up = acc[ai][1][m][n][i] * rs;
;                         a[n * 4 + i] = g * __builtin_amdgcn_rcpf(1.0f + __builtin_amdgcn_exp2f(-1.4426950408889634f * g)) * up; }
;                 u32x4 w; w.x = cvt_pk_bf16(a[0], a[1]); w.y = cvt_pk_bf16(a[2], a[3]); w.z = cvt_pk_bf16(a[4], a[5]); w.w = cvt_pk_bf16(a[6], a[7]);
;                 *(u32x4*)(O + (size_t)row * ldc + col0) = w; }
	v_add_f32_e32 v151, 1.0, v151
	v_rcp_f32_e32 v144, v144
	v_rcp_f32_e32 v145, v145
	v_rcp_f32_e32 v146, v146
	v_rcp_f32_e32 v147, v147
	v_rcp_f32_e32 v148, v148
	v_rcp_f32_e32 v149, v149
	v_rcp_f32_e32 v150, v150
	v_rcp_f32_e32 v151, v151
	v_mul_f32_e32 v64, v64, v144
	v_mul_f32_e32 v65, v65, v145
	v_mul_f32_e32 v66, v66, v146
	v_mul_f32_e32 v67, v67, v147
	v_mul_f32_e32 v68, v68, v148
	v_mul_f32_e32 v69, v69, v149
	v_mul_f32_e32 v70, v70, v150
	v_mul_f32_e32 v71, v71, v151
	v_mul_f32_e32 v64, v96, v64
	v_mul_f32_e32 v65, v97, v65
	v_mul_f32_e32 v66, v98, v66
	v_mul_f32_e32 v67, v99, v67
	v_mul_f32_e32 v68, v100, v68
	v_mul_f32_e32 v69, v101, v69
	v_mul_f32_e32 v70, v102, v70
	v_mul_f32_e32 v71, v103, v71
	v_cvt_pk_bf16_f32 v152, v64, v65
	v_cvt_pk_bf16_f32 v153, v66, v67
	v_cvt_pk_bf16_f32 v154, v68, v69
	v_cvt_pk_bf16_f32 v155, v70, v71
	s_nop 1
	global_store_dwordx4 v132, v[152:155], s[50:51]
	s_nop 1
	v_fmamk_f32 v131, v139, 0x3a000000, v130
	v_add_u32_e32 v132, 0x18c000, v129
	v_rsq_f32_e32 v131, v131
	s_nop 0
	v_mul_f32_e32 v72, v72, v131
	v_mul_f32_e32 v73, v73, v131
	v_mul_f32_e32 v74, v74, v131
	v_mul_f32_e32 v75, v75, v131
	v_mul_f32_e32 v76, v76, v131
	v_mul_f32_e32 v77, v77, v131
	v_mul_f32_e32 v78, v78, v131
	v_mul_f32_e32 v79, v79, v131
	v_mul_f32_e32 v104, v104, v131
	v_mul_f32_e32 v105, v105, v131
	v_mul_f32_e32 v106, v106, v131
	v_mul_f32_e32 v107, v107, v131
	v_mul_f32_e32 v108, v108, v131
	v_mul_f32_e32 v109, v109, v131
	v_mul_f32_e32 v110, v110, v131
	v_mul_f32_e32 v111, v111, v131
	v_mul_f32_e32 v144, 0xbfb8aa3b, v72
	v_mul_f32_e32 v145, 0xbfb8aa3b, v73
	v_mul_f32_e32 v146, 0xbfb8aa3b, v74
	v_mul_f32_e32 v147, 0xbfb8aa3b, v75
	v_mul_f32_e32 v148, 0xbfb8aa3b, v76
	v_mul_f32_e32 v149, 0xbfb8aa3b, v77
	v_mul_f32_e32 v150, 0xbfb8aa3b, v78
	v_mul_f32_e32 v151, 0xbfb8aa3b, v79
	v_exp_f32_e32 v144, v144
	v_exp_f32_e32 v145, v145
	v_exp_f32_e32 v146, v146
	v_exp_f32_e32 v147, v147
	v_exp_f32_e32 v148, v148
	v_exp_f32_e32 v149, v149
	v_exp_f32_e32 v150, v150
	v_exp_f32_e32 v151, v151
	v_add_f32_e32 v144, 1.0, v144
	v_add_f32_e32 v145, 1.0, v145
	v_add_f32_e32 v146, 1.0, v146
	v_add_f32_e32 v147, 1.0, v147
	v_add_f32_e32 v148, 1.0, v148
	v_add_f32_e32 v149, 1.0, v149
	v_add_f32_e32 v150, 1.0, v150
	v_add_f32_e32 v151, 1.0, v151
	v_rcp_f32_e32 v144, v144
	v_rcp_f32_e32 v145, v145
	v_rcp_f32_e32 v146, v146
	v_rcp_f32_e32 v147, v147
	v_rcp_f32_e32 v148, v148
	v_rcp_f32_e32 v149, v149
	v_rcp_f32_e32 v150, v150
	v_rcp_f32_e32 v151, v151
	v_mul_f32_e32 v72, v72, v144
	v_mul_f32_e32 v73, v73, v145
	v_mul_f32_e32 v74, v74, v146
	v_mul_f32_e32 v75, v75, v147
	v_mul_f32_e32 v76, v76, v148
	v_mul_f32_e32 v77, v77, v149
	v_mul_f32_e32 v78, v78, v150
	v_mul_f32_e32 v79, v79, v151
	v_mul_f32_e32 v72, v104, v72
	v_mul_f32_e32 v73, v105, v73
	v_mul_f32_e32 v74, v106, v74
	v_mul_f32_e32 v75, v107, v75
	v_mul_f32_e32 v76, v108, v76
	v_mul_f32_e32 v77, v109, v77
	v_mul_f32_e32 v78, v110, v78
	v_mul_f32_e32 v79, v111, v79
	v_cvt_pk_bf16_f32 v152, v72, v73
	v_cvt_pk_bf16_f32 v153, v74, v75
	v_cvt_pk_bf16_f32 v154, v76, v77
	v_cvt_pk_bf16_f32 v155, v78, v79
	s_nop 1
	global_store_dwordx4 v132, v[152:155], s[50:51]
	s_nop 1
	v_fmamk_f32 v131, v140, 0x3a000000, v130
	v_add_u32_e32 v132, 0x1b8000, v129
	v_rsq_f32_e32 v131, v131
	s_nop 0
	v_mul_f32_e32 v80, v80, v131
	v_mul_f32_e32 v81, v81, v131
	v_mul_f32_e32 v82, v82, v131
	v_mul_f32_e32 v83, v83, v131
	v_mul_f32_e32 v84, v84, v131
	v_mul_f32_e32 v85, v85, v131
	v_mul_f32_e32 v86, v86, v131
	v_mul_f32_e32 v87, v87, v131
	v_mul_f32_e32 v112, v112, v131
	v_mul_f32_e32 v113, v113, v131
	v_mul_f32_e32 v114, v114, v131
	v_mul_f32_e32 v115, v115, v131
	v_mul_f32_e32 v116, v116, v131
	v_mul_f32_e32 v117, v117, v131
	v_mul_f32_e32 v118, v118, v131
	v_mul_f32_e32 v119, v119, v131
	v_mul_f32_e32 v144, 0xbfb8aa3b, v80
	v_mul_f32_e32 v145, 0xbfb8aa3b, v81
	v_mul_f32_e32 v146, 0xbfb8aa3b, v82
	v_mul_f32_e32 v147, 0xbfb8aa3b, v83
; __device__ __forceinline__ unsigned cvt_pk_bf16(float lo, float hi) { unsigned r; asm volatile("v_cvt_pk_bf16_f32 %0, %1, %2" : "=v"(r) : "v"(lo), "v"(hi)); return r; }
;     __device__ __forceinline__ void operator()(const f32x4 (&acc)[2][2][4][2], const Unit& u, int wr, int wc, int fr, int fq) const {
;     ...
;         for (int ai = 0; ai < 2; ++ai)
; #pragma unroll
;             for (int m = 0; m < 4; ++m) { const int row = row0 + ai * HALF + m * 16; const float rs = __builtin_amdgcn_rsqf(rsv[ai][m] * inv_n + eps);
;                 float a[8];
; #pragma unroll
;                 for (int n = 0; n < 2; ++n)
; #pragma unroll
;                     for (int i = 0; i < 4; ++i) { const float g = acc[ai][0][m][n][i] * rs, up = acc[ai][1][m][n][i] * rs;
;                         a[n * 4 + i] = g * __builtin_amdgcn_rcpf(1.0f + __builtin_amdgcn_exp2f(-1.4426950408889634f * g)) * up; }
;                 u32x4 w; w.x = cvt_pk_bf16(a[0], a[1]); w.y = cvt_pk_bf16(a[2], a[3]); w.z = cvt_pk_bf16(a[4], a[5]); w.w = cvt_pk_bf16(a[6], a[7]);
;                 *(u32x4*)(O + (size_t)row * ldc + col0) = w; }
; template <class Epi, class Sched, bool ALIGN_EPI = false, bool SP2 = false>
; __device__ __forceinline__ void gemm_phase(PG8_LAS unsigned char* lds, const Gemm g, const Sched& S, const Epi& E) {
;     ...
;         if (!has_next) break;
; #pragma unroll
;         for (int a = 0; a < 2; ++a)
; #pragma unroll
;             for (int b = 0; b < 2; ++b)
; #pragma unroll
;                 for (int m = 0; m < 4; ++m)
; #pragma unroll
;                     for (int n = 0; n < 2; ++n) acc[a][b][m][n] = (f32x4){0.f, 0.f, 0.f, 0.f};
;         cur = nxt; cA = nA; cB = nB; ++ui;
	v_mul_f32_e32 v148, 0xbfb8aa3b, v84
	v_mul_f32_e32 v149, 0xbfb8aa3b, v85
	v_mul_f32_e32 v150, 0xbfb8aa3b, v86
	v_mul_f32_e32 v151, 0xbfb8aa3b, v87
	v_exp_f32_e32 v144, v144
	v_exp_f32_e32 v145, v145
	v_exp_f32_e32 v146, v146
	v_exp_f32_e32 v147, v147
	v_exp_f32_e32 v148, v148
	v_exp_f32_e32 v149, v149
	v_exp_f32_e32 v150, v150
	v_exp_f32_e32 v151, v151
	v_add_f32_e32 v144, 1.0, v144
	v_add_f32_e32 v145, 1.0, v145
	v_add_f32_e32 v146, 1.0, v146
	v_add_f32_e32 v147, 1.0, v147
	v_add_f32_e32 v148, 1.0, v148
	v_add_f32_e32 v149, 1.0, v149
	v_add_f32_e32 v150, 1.0, v150
	v_add_f32_e32 v151, 1.0, v151
	v_rcp_f32_e32 v144, v144
	v_rcp_f32_e32 v145, v145
	v_rcp_f32_e32 v146, v146
	v_rcp_f32_e32 v147, v147
	v_rcp_f32_e32 v148, v148
	v_rcp_f32_e32 v149, v149
	v_rcp_f32_e32 v150, v150
	v_rcp_f32_e32 v151, v151
	v_mul_f32_e32 v80, v80, v144
	v_mul_f32_e32 v81, v81, v145
	v_mul_f32_e32 v82, v82, v146
	v_mul_f32_e32 v83, v83, v147
	v_mul_f32_e32 v84, v84, v148
	v_mul_f32_e32 v85, v85, v149
	v_mul_f32_e32 v86, v86, v150
	v_mul_f32_e32 v87, v87, v151
	v_mul_f32_e32 v80, v112, v80
	v_mul_f32_e32 v81, v113, v81
	v_mul_f32_e32 v82, v114, v82
	v_mul_f32_e32 v83, v115, v83
	v_mul_f32_e32 v84, v116, v84
	v_mul_f32_e32 v85, v117, v85
	v_mul_f32_e32 v86, v118, v86
	v_mul_f32_e32 v87, v119, v87
	v_cvt_pk_bf16_f32 v152, v80, v81
	v_cvt_pk_bf16_f32 v153, v82, v83
	v_cvt_pk_bf16_f32 v154, v84, v85
	v_cvt_pk_bf16_f32 v155, v86, v87
	s_nop 1
	global_store_dwordx4 v132, v[152:155], s[50:51]
	s_nop 1
	v_fmamk_f32 v131, v141, 0x3a000000, v130
	v_add_u32_e32 v132, 0x1e4000, v129
	v_rsq_f32_e32 v131, v131
	s_nop 0
	v_mul_f32_e32 v88, v88, v131
	v_mul_f32_e32 v89, v89, v131
	v_mul_f32_e32 v90, v90, v131
	v_mul_f32_e32 v91, v91, v131
	v_mul_f32_e32 v92, v92, v131
	v_mul_f32_e32 v93, v93, v131
	v_mul_f32_e32 v94, v94, v131
	v_mul_f32_e32 v95, v95, v131
	v_mul_f32_e32 v120, v120, v131
	v_mul_f32_e32 v121, v121, v131
	v_mul_f32_e32 v122, v122, v131
	v_mul_f32_e32 v123, v123, v131
	v_mul_f32_e32 v124, v124, v131
	v_mul_f32_e32 v125, v125, v131
	v_mul_f32_e32 v126, v126, v131
	v_mul_f32_e32 v127, v127, v131
	v_mul_f32_e32 v144, 0xbfb8aa3b, v88
	v_mul_f32_e32 v145, 0xbfb8aa3b, v89
	v_mul_f32_e32 v146, 0xbfb8aa3b, v90
	v_mul_f32_e32 v147, 0xbfb8aa3b, v91
	v_mul_f32_e32 v148, 0xbfb8aa3b, v92
	v_mul_f32_e32 v149, 0xbfb8aa3b, v93
	v_mul_f32_e32 v150, 0xbfb8aa3b, v94
	v_mul_f32_e32 v151, 0xbfb8aa3b, v95
	v_exp_f32_e32 v144, v144
	v_exp_f32_e32 v145, v145
	v_exp_f32_e32 v146, v146
	v_exp_f32_e32 v147, v147
	v_exp_f32_e32 v148, v148
	v_exp_f32_e32 v149, v149
	v_exp_f32_e32 v150, v150
	v_exp_f32_e32 v151, v151
	v_add_f32_e32 v144, 1.0, v144
	v_add_f32_e32 v145, 1.0, v145
	v_add_f32_e32 v146, 1.0, v146
	v_add_f32_e32 v147, 1.0, v147
	v_add_f32_e32 v148, 1.0, v148
	v_add_f32_e32 v149, 1.0, v149
	v_add_f32_e32 v150, 1.0, v150
	v_add_f32_e32 v151, 1.0, v151
	v_rcp_f32_e32 v144, v144
	v_rcp_f32_e32 v145, v145
	v_rcp_f32_e32 v146, v146
	v_rcp_f32_e32 v147, v147
	v_rcp_f32_e32 v148, v148
	v_rcp_f32_e32 v149, v149
	v_rcp_f32_e32 v150, v150
	v_rcp_f32_e32 v151, v151
	v_mul_f32_e32 v88, v88, v144
	v_mul_f32_e32 v89, v89, v145
	v_mul_f32_e32 v90, v90, v146
	v_mul_f32_e32 v91, v91, v147
	v_mul_f32_e32 v92, v92, v148
	v_mul_f32_e32 v93, v93, v149
	v_mul_f32_e32 v94, v94, v150
	v_mul_f32_e32 v95, v95, v151
	v_mul_f32_e32 v88, v120, v88
	v_mul_f32_e32 v89, v121, v89
	v_mul_f32_e32 v90, v122, v90
	v_mul_f32_e32 v91, v123, v91
	v_mul_f32_e32 v92, v124, v92
	v_mul_f32_e32 v93, v125, v93
	v_mul_f32_e32 v94, v126, v94
	v_mul_f32_e32 v95, v127, v95
	v_cvt_pk_bf16_f32 v152, v88, v89
	v_cvt_pk_bf16_f32 v153, v90, v91
	v_cvt_pk_bf16_f32 v154, v92, v93
	v_cvt_pk_bf16_f32 v155, v94, v95
	s_nop 1
	global_store_dwordx4 v132, v[152:155], s[50:51]
	s_nop 1
	s_cmp_eq_u32 s19, 0
	s_cbranch_scc1 .Lp5_done
	s_mov_b32 s17, s20
	s_mov_b32 s18, s21
	s_mov_b64 s[22:23], s[26:27]
	s_mov_b64 s[24:25], s[28:29]
	s_add_u32 s16, s16, 1
	s_branch .Lp5_unit

; template <class Epi, class Sched, bool ALIGN_EPI = false, bool SP2 = false>
; __device__ __forceinline__ void gemm_phase(PG8_LAS unsigned char* lds, const Gemm g, const Sched& S, const Epi& E) {
;     ...
;     if (!S.next(0, cur)) return;
.Lp5_exit:
	v_readlane_b32 s40, v253, 60
	v_readlane_b32 s41, v253, 61
	s_nop 3
	s_mov_b32 vcc_lo, s40
	s_mov_b32 vcc_hi, s41
	v_readlane_b32 s4, v253, 0
	v_readlane_b32 s5, v253, 1
	v_readlane_b32 s6, v253, 2
	v_readlane_b32 s7, v253, 3
	v_readlane_b32 s8, v253, 4
	v_readlane_b32 s9, v253, 5
	v_readlane_b32 s10, v253, 6
	v_readlane_b32 s11, v253, 7
	v_readlane_b32 s12, v253, 8
	v_readlane_b32 s13, v253, 9
	v_readlane_b32 s14, v253, 10
	v_readlane_b32 s15, v253, 11
	v_readlane_b32 s16, v253, 12
	v_readlane_b32 s17, v253, 13
	v_readlane_b32 s18, v253, 14
	v_readlane_b32 s19, v253, 15
	v_readlane_b32 s20, v253, 16
	v_readlane_b32 s21, v253, 17
	v_readlane_b32 s22, v253, 18
	v_readlane_b32 s23, v253, 19
	v_readlane_b32 s24, v253, 20
	v_readlane_b32 s25, v253, 21
	v_readlane_b32 s26, v253, 22
	v_readlane_b32 s27, v253, 23
	v_readlane_b32 s28, v253, 24
	v_readlane_b32 s29, v253, 25
	v_readlane_b32 s30, v253, 26
	v_readlane_b32 s31, v253, 27
	v_readlane_b32 s32, v253, 28
	v_readlane_b32 s33, v253, 29
	v_readlane_b32 s34, v253, 30
	v_readlane_b32 s35, v253, 31
	v_readlane_b32 s36, v253, 32
	v_readlane_b32 s37, v253, 33
	v_readlane_b32 s38, v253, 34
	v_readlane_b32 s39, v253, 35
	v_readlane_b32 s40, v253, 36
	v_readlane_b32 s41, v253, 37
	v_readlane_b32 s42, v253, 38
	v_readlane_b32 s43, v253, 39
	v_readlane_b32 s44, v253, 40
	v_readlane_b32 s45, v253, 41
	v_readlane_b32 s46, v253, 42
	v_readlane_b32 s47, v253, 43
	v_readlane_b32 s48, v253, 44
	v_readlane_b32 s49, v253, 45
	v_readlane_b32 s50, v253, 46
	v_readlane_b32 s51, v253, 47
	v_readlane_b32 s52, v253, 48
	v_readlane_b32 s53, v253, 49
	v_readlane_b32 s54, v253, 50
	v_readlane_b32 s55, v253, 51
	v_readlane_b32 s56, v253, 52
	v_readlane_b32 s57, v253, 53
	v_readlane_b32 s58, v253, 54
	v_readlane_b32 s59, v253, 55
	s_nop 7

; __global__ void __launch_bounds__(NWAVES * 64, 2) hybrid_fwd(Args args) {
	.amdhsa_kernel _Z10hybrid_fwd4Args
		.amdhsa_group_segment_fixed_size 0
		.amdhsa_private_segment_fixed_size 0
		.amdhsa_kernarg_size 352
		.amdhsa_user_sgpr_count 2
		.amdhsa_user_sgpr_dispatch_ptr 0
		.amdhsa_user_sgpr_queue_ptr 0
		.amdhsa_user_sgpr_kernarg_segment_ptr 1
		.amdhsa_user_sgpr_dispatch_id 0
		.amdhsa_user_sgpr_kernarg_preload_length 0
		.amdhsa_user_sgpr_kernarg_preload_offset 0
		.amdhsa_user_sgpr_private_segment_size 0
		.amdhsa_uses_dynamic_stack 0
		.amdhsa_enable_private_segment 0
		.amdhsa_system_sgpr_workgroup_id_x 1
		.amdhsa_system_sgpr_workgroup_id_y 0
		.amdhsa_system_sgpr_workgroup_id_z 0
		.amdhsa_system_sgpr_workgroup_info 0
		.amdhsa_system_vgpr_workitem_id 2
		.amdhsa_next_free_vgpr 256
		.amdhsa_next_free_sgpr 98
		.amdhsa_accum_offset 256
		.amdhsa_reserve_vcc 1
		.amdhsa_float_round_mode_32 0
		.amdhsa_float_round_mode_16_64 0
		.amdhsa_float_denorm_mode_32 3
		.amdhsa_float_denorm_mode_16_64 3
		.amdhsa_dx10_clamp 1
		.amdhsa_ieee_mode 1
		.amdhsa_fp16_overflow 0
		.amdhsa_tg_split 0
		.amdhsa_exception_fp_ieee_invalid_op 0
		.amdhsa_exception_fp_denorm_src 0
		.amdhsa_exception_fp_ieee_div_zero 0
		.amdhsa_exception_fp_ieee_overflow 0
		.amdhsa_exception_fp_ieee_underflow 0
		.amdhsa_exception_fp_ieee_inexact 0
		.amdhsa_exception_int_div_zero 0
	.end_amdhsa_kernel

; __global__ void __launch_bounds__(NWAVES * 64, 2) hybrid_fwd(Args args) {
.Lfunc_end0:
	.size	_Z10hybrid_fwd4Args, .Lfunc_end0-_Z10hybrid_fwd4Args
	.set _Z10hybrid_fwd4Args.num_vgpr, 256
	.set _Z10hybrid_fwd4Args.num_agpr, 0
	.set _Z10hybrid_fwd4Args.numbered_sgpr, 98
	.set _Z10hybrid_fwd4Args.num_named_barrier, 0
	.set _Z10hybrid_fwd4Args.private_seg_size, 0
	.set _Z10hybrid_fwd4Args.uses_vcc, 1
	.set _Z10hybrid_fwd4Args.uses_flat_scratch, 0
	.set _Z10hybrid_fwd4Args.has_dyn_sized_stack, 0
	.set _Z10hybrid_fwd4Args.has_recursion, 0
	.set _Z10hybrid_fwd4Args.has_indirect_call, 0

; __global__ void __launch_bounds__(NWAVES * 64, 2) hybrid_fwd(Args args) {
amdhsa.kernels:
  - .agpr_count:     0
    .args:
      - .offset:         0
        .size:           96
        .value_kind:     by_value
      - .offset:         96
        .size:           4
        .value_kind:     hidden_block_count_x
      - .offset:         100
        .size:           4
        .value_kind:     hidden_block_count_y
      - .offset:         104
        .size:           4
        .value_kind:     hidden_block_count_z
      - .offset:         108
        .size:           2
        .value_kind:     hidden_group_size_x
      - .offset:         110
        .size:           2
        .value_kind:     hidden_group_size_y
      - .offset:         112
        .size:           2
        .value_kind:     hidden_group_size_z
      - .offset:         114
        .size:           2
        .value_kind:     hidden_remainder_x
      - .offset:         116
        .size:           2
        .value_kind:     hidden_remainder_y
      - .offset:         118
        .size:           2
        .value_kind:     hidden_remainder_z
      - .offset:         136
        .size:           8
        .value_kind:     hidden_global_offset_x
      - .offset:         144
        .size:           8
        .value_kind:     hidden_global_offset_y
      - .offset:         152
        .size:           8
        .value_kind:     hidden_global_offset_z
      - .offset:         160
        .size:           2
        .value_kind:     hidden_grid_dims
      - .offset:         184
        .size:           8
        .value_kind:     hidden_multigrid_sync_arg
      - .offset:         216
        .size:           4
        .value_kind:     hidden_dynamic_lds_size
    .group_segment_fixed_size: 0
    .kernarg_segment_align: 8
    .kernarg_segment_size: 352
    .language:       OpenCL C
    .language_version:
      - 2
      - 0
    .max_flat_workgroup_size: 512
    .name:           _Z10hybrid_fwd4Args
    .private_segment_fixed_size: 0
    .sgpr_count:     104
    .sgpr_spill_count: 45
    .symbol:         _Z10hybrid_fwd4Args.kd
    .uniform_work_group_size: 1
    .uses_dynamic_stack: false
    .vgpr_count:     256
    .vgpr_spill_count: 0
    .wavefront_size: 64
